# hand-written final LayerNorm pass with the exact counted wait (vmcnt 27: full three-row prefetch lead)
# baseline (speedup 1.0000x reference)
.Lln2_loop:
	global_load_dwordx4 v[108:111], v[232:233], off
	global_load_dwordx4 v[112:115], v[232:233], off offset:1024
	global_load_dwordx4 v[116:119], v[234:235], off
	global_load_dwordx4 v[120:123], v[234:235], off offset:1024
	global_load_dwordx2 v[124:125], v[236:237], off
	s_cmp_lt_u32 s33, 28
	s_cselect_b32 s44, s40, 0
	s_cselect_b32 s46, s42, 0
	s_mov_b32 s45, 0
	s_mov_b32 s47, 0
	v_lshl_add_u64 v[232:233], v[232:233], 0, s[44:45]
	v_lshl_add_u64 v[234:235], v[234:235], 0, s[44:45]
	v_lshl_add_u64 v[236:237], v[236:237], 0, s[46:47]
	s_waitcnt vmcnt(27)
	v_lshlrev_b32_e32 v16, 16, v56
	v_and_b32_e32 v17, 0xffff0000, v56
	v_lshlrev_b32_e32 v0, 16, v48
	v_and_b32_e32 v1, 0xffff0000, v48
	v_sub_f32_e32 v16, v16, v64
	v_sub_f32_e32 v17, v17, v64
	v_mul_f32_e32 v16, v16, v65
	v_mul_f32_e32 v17, v17, v65
	v_fma_f32 v16, v16, v128, v144
	v_fma_f32 v17, v17, v129, v145
	v_fma_f32 v0, v16, s14, v0
	v_fma_f32 v1, v17, s14, v1
	v_lshlrev_b32_e32 v18, 16, v57
	v_and_b32_e32 v19, 0xffff0000, v57
	v_lshlrev_b32_e32 v2, 16, v49
	v_and_b32_e32 v3, 0xffff0000, v49
	v_sub_f32_e32 v18, v18, v64
	v_sub_f32_e32 v19, v19, v64
	v_mul_f32_e32 v18, v18, v65
	v_mul_f32_e32 v19, v19, v65
	v_fma_f32 v18, v18, v130, v146
	v_fma_f32 v19, v19, v131, v147
	v_fma_f32 v2, v18, s14, v2
	v_fma_f32 v3, v19, s14, v3
	v_lshlrev_b32_e32 v20, 16, v58
	v_and_b32_e32 v21, 0xffff0000, v58
	v_lshlrev_b32_e32 v4, 16, v50
	v_and_b32_e32 v5, 0xffff0000, v50
	v_sub_f32_e32 v20, v20, v64
	v_sub_f32_e32 v21, v21, v64
	v_mul_f32_e32 v20, v20, v65
	v_mul_f32_e32 v21, v21, v65
	v_fma_f32 v20, v20, v132, v148
	v_fma_f32 v21, v21, v133, v149
	v_fma_f32 v4, v20, s14, v4
	v_fma_f32 v5, v21, s14, v5
	v_lshlrev_b32_e32 v22, 16, v59
	v_and_b32_e32 v23, 0xffff0000, v59
	v_lshlrev_b32_e32 v6, 16, v51
	v_and_b32_e32 v7, 0xffff0000, v51
	v_sub_f32_e32 v22, v22, v64
	v_sub_f32_e32 v23, v23, v64
	v_mul_f32_e32 v22, v22, v65
	v_mul_f32_e32 v23, v23, v65
	v_fma_f32 v22, v22, v134, v150
	v_fma_f32 v23, v23, v135, v151
	v_fma_f32 v6, v22, s14, v6
	v_fma_f32 v7, v23, s14, v7
	v_lshlrev_b32_e32 v24, 16, v60
	v_and_b32_e32 v25, 0xffff0000, v60
	v_lshlrev_b32_e32 v8, 16, v52
	v_and_b32_e32 v9, 0xffff0000, v52
	v_sub_f32_e32 v24, v24, v64
	v_sub_f32_e32 v25, v25, v64
	v_mul_f32_e32 v24, v24, v65
	v_mul_f32_e32 v25, v25, v65
	v_fma_f32 v24, v24, v136, v152
	v_fma_f32 v25, v25, v137, v153
	v_fma_f32 v8, v24, s14, v8
	v_fma_f32 v9, v25, s14, v9
	v_lshlrev_b32_e32 v26, 16, v61
	v_and_b32_e32 v27, 0xffff0000, v61
	v_lshlrev_b32_e32 v10, 16, v53
	v_and_b32_e32 v11, 0xffff0000, v53
	v_sub_f32_e32 v26, v26, v64
	v_sub_f32_e32 v27, v27, v64
	v_mul_f32_e32 v26, v26, v65
	v_mul_f32_e32 v27, v27, v65
	v_fma_f32 v26, v26, v138, v154
	v_fma_f32 v27, v27, v139, v155
	v_fma_f32 v10, v26, s14, v10
	v_fma_f32 v11, v27, s14, v11
	v_lshlrev_b32_e32 v28, 16, v62
	v_and_b32_e32 v29, 0xffff0000, v62
	v_lshlrev_b32_e32 v12, 16, v54
	v_and_b32_e32 v13, 0xffff0000, v54
	v_sub_f32_e32 v28, v28, v64
	v_sub_f32_e32 v29, v29, v64
	v_mul_f32_e32 v28, v28, v65
	v_mul_f32_e32 v29, v29, v65
	v_fma_f32 v28, v28, v140, v156
	v_fma_f32 v29, v29, v141, v157
	v_fma_f32 v12, v28, s14, v12
	v_fma_f32 v13, v29, s14, v13
	v_lshlrev_b32_e32 v30, 16, v63
	v_and_b32_e32 v31, 0xffff0000, v63
	v_lshlrev_b32_e32 v14, 16, v55
	v_and_b32_e32 v15, 0xffff0000, v55
	v_sub_f32_e32 v30, v30, v64
	v_sub_f32_e32 v31, v31, v64
	v_mul_f32_e32 v30, v30, v65
	v_mul_f32_e32 v31, v31, v65
	v_fma_f32 v30, v30, v142, v158
	v_fma_f32 v31, v31, v143, v159
	v_fma_f32 v14, v30, s14, v14
	v_fma_f32 v15, v31, s14, v15
	v_add_f32_e32 v16, v0, v1
	v_add_f32_e32 v17, v2, v3
	v_add_f32_e32 v18, v4, v5
	v_add_f32_e32 v19, v6, v7
	v_add_f32_e32 v20, v8, v9
	v_add_f32_e32 v21, v10, v11
	v_add_f32_e32 v22, v12, v13
	v_add_f32_e32 v23, v14, v15
	v_add_f32_e32 v16, v16, v17
	v_add_f32_e32 v18, v18, v19
	v_add_f32_e32 v20, v20, v21
	v_add_f32_e32 v22, v22, v23
	v_add_f32_e32 v16, v16, v18
	v_add_f32_e32 v20, v20, v22
	v_add_f32_e32 v32, v16, v20
	v_mov_b32_e32 v34, v32
	s_nop 1
	v_add_f32_dpp v34, v32, v32 quad_perm:[1,0,3,2] row_mask:0xf bank_mask:0xf
	s_nop 1
	v_add_f32_dpp v34, v34, v34 quad_perm:[2,3,0,1] row_mask:0xf bank_mask:0xf
	s_nop 1
	v_add_f32_dpp v34, v34, v34 row_half_mirror row_mask:0xf bank_mask:0xf
	s_nop 1
	v_add_f32_dpp v34, v34, v34 row_mirror row_mask:0xf bank_mask:0xf
	s_nop 1
	v_add_f32_dpp v34, v34, v34 row_bcast:15 row_mask:0xa bank_mask:0xf
	s_nop 1
	v_add_f32_dpp v34, v34, v34 row_bcast:31 row_mask:0xc bank_mask:0xf
	s_nop 1
	v_readlane_b32 s0, v34, 63
	s_nop 0
	v_mov_b32_e32 v33, 0x3a800000
	v_mul_f32_e32 v33, s0, v33
	v_sub_f32_e32 v0, v0, v33
	v_sub_f32_e32 v1, v1, v33
	v_sub_f32_e32 v2, v2, v33
	v_sub_f32_e32 v3, v3, v33
	v_sub_f32_e32 v4, v4, v33
	v_sub_f32_e32 v5, v5, v33
	v_sub_f32_e32 v6, v6, v33
	v_sub_f32_e32 v7, v7, v33
	v_sub_f32_e32 v8, v8, v33
	v_sub_f32_e32 v9, v9, v33
	v_sub_f32_e32 v10, v10, v33
	v_sub_f32_e32 v11, v11, v33
	v_sub_f32_e32 v12, v12, v33
	v_sub_f32_e32 v13, v13, v33
	v_sub_f32_e32 v14, v14, v33
	v_sub_f32_e32 v15, v15, v33
	v_mul_f32_e32 v16, v0, v0
	v_fmac_f32_e32 v16, v1, v1
	v_mul_f32_e32 v17, v2, v2
	v_fmac_f32_e32 v17, v3, v3
	v_mul_f32_e32 v18, v4, v4
	v_fmac_f32_e32 v18, v5, v5
	v_mul_f32_e32 v19, v6, v6
	v_fmac_f32_e32 v19, v7, v7
	v_mul_f32_e32 v20, v8, v8
	v_fmac_f32_e32 v20, v9, v9
	v_mul_f32_e32 v21, v10, v10
	v_fmac_f32_e32 v21, v11, v11
	v_mul_f32_e32 v22, v12, v12
	v_fmac_f32_e32 v22, v13, v13
	v_mul_f32_e32 v23, v14, v14
	v_fmac_f32_e32 v23, v15, v15
	v_add_f32_e32 v16, v16, v17
	v_add_f32_e32 v18, v18, v19
	v_add_f32_e32 v20, v20, v21
	v_add_f32_e32 v22, v22, v23
	v_add_f32_e32 v16, v16, v18
	v_add_f32_e32 v20, v20, v22
	v_add_f32_e32 v32, v16, v20
	v_mov_b32_e32 v34, v32
	s_nop 1
	v_add_f32_dpp v34, v32, v32 quad_perm:[1,0,3,2] row_mask:0xf bank_mask:0xf
	s_nop 1
	v_add_f32_dpp v34, v34, v34 quad_perm:[2,3,0,1] row_mask:0xf bank_mask:0xf
	s_nop 1
	v_add_f32_dpp v34, v34, v34 row_half_mirror row_mask:0xf bank_mask:0xf
	s_nop 1
	v_add_f32_dpp v34, v34, v34 row_mirror row_mask:0xf bank_mask:0xf
	s_nop 1
	v_add_f32_dpp v34, v34, v34 row_bcast:15 row_mask:0xa bank_mask:0xf
	s_nop 1
	v_add_f32_dpp v34, v34, v34 row_bcast:31 row_mask:0xc bank_mask:0xf
	s_nop 1
	v_readlane_b32 s0, v34, 63
	s_nop 0
	v_mov_b32_e32 v33, 0x3a800000
	v_mov_b32_e32 v35, 0x3727c5ac
	v_fma_f32 v33, s0, v33, v35
	v_rsq_f32_e32 v33, v33
	s_nop 0
	v_mul_f32_e32 v0, v0, v33
	v_mul_f32_e32 v1, v1, v33
	v_mul_f32_e32 v2, v2, v33
	v_mul_f32_e32 v3, v3, v33
	v_fma_f32 v0, v0, v160, v176
	v_fma_f32 v1, v1, v161, v177
	v_fma_f32 v2, v2, v162, v178
	v_fma_f32 v3, v3, v163, v179
	v_mul_f32_e32 v4, v4, v33
	v_mul_f32_e32 v5, v5, v33
	v_mul_f32_e32 v6, v6, v33
	v_mul_f32_e32 v7, v7, v33
	v_fma_f32 v4, v4, v164, v180
	v_fma_f32 v5, v5, v165, v181
	v_fma_f32 v6, v6, v166, v182
	v_fma_f32 v7, v7, v167, v183
	v_mul_f32_e32 v8, v8, v33
	v_mul_f32_e32 v9, v9, v33
	v_mul_f32_e32 v10, v10, v33
	v_mul_f32_e32 v11, v11, v33
	v_fma_f32 v8, v8, v168, v184
	v_fma_f32 v9, v9, v169, v185
	v_fma_f32 v10, v10, v170, v186
	v_fma_f32 v11, v11, v171, v187
	v_mul_f32_e32 v12, v12, v33
	v_mul_f32_e32 v13, v13, v33
	v_mul_f32_e32 v14, v14, v33
	v_mul_f32_e32 v15, v15, v33
	v_fma_f32 v12, v12, v172, v188
	v_fma_f32 v13, v13, v173, v189
	v_fma_f32 v14, v14, v174, v190
	v_fma_f32 v15, v15, v175, v191
	global_store_dwordx4 v[238:239], v[0:3], off
	global_store_dwordx4 v[238:239], v[4:7], off offset:16
	global_store_dwordx4 v[238:239], v[8:11], off offset:2048
	global_store_dwordx4 v[238:239], v[12:15], off offset:2064
	s_mov_b32 s44, 0x800000
	s_mov_b32 s45, 0
	v_lshl_add_u64 v[238:239], v[238:239], 0, s[44:45]
	s_add_u32 s33, s33, 1
	global_load_dwordx4 v[48:51], v[232:233], off
	global_load_dwordx4 v[52:55], v[232:233], off offset:1024
	global_load_dwordx4 v[56:59], v[234:235], off
	global_load_dwordx4 v[60:63], v[234:235], off offset:1024
	global_load_dwordx2 v[64:65], v[236:237], off
	s_cmp_lt_u32 s33, 28
	s_cselect_b32 s44, s40, 0
	s_cselect_b32 s46, s42, 0
	s_mov_b32 s45, 0
	s_mov_b32 s47, 0
	v_lshl_add_u64 v[232:233], v[232:233], 0, s[44:45]
	v_lshl_add_u64 v[234:235], v[234:235], 0, s[44:45]
	v_lshl_add_u64 v[236:237], v[236:237], 0, s[46:47]
	s_waitcnt vmcnt(27)
	v_lshlrev_b32_e32 v16, 16, v76
	v_and_b32_e32 v17, 0xffff0000, v76
	v_lshlrev_b32_e32 v0, 16, v68
	v_and_b32_e32 v1, 0xffff0000, v68
	v_sub_f32_e32 v16, v16, v84
	v_sub_f32_e32 v17, v17, v84
	v_mul_f32_e32 v16, v16, v85
	v_mul_f32_e32 v17, v17, v85
	v_fma_f32 v16, v16, v128, v144
	v_fma_f32 v17, v17, v129, v145
	v_fma_f32 v0, v16, s14, v0
	v_fma_f32 v1, v17, s14, v1
	v_lshlrev_b32_e32 v18, 16, v77
	v_and_b32_e32 v19, 0xffff0000, v77
	v_lshlrev_b32_e32 v2, 16, v69
	v_and_b32_e32 v3, 0xffff0000, v69
	v_sub_f32_e32 v18, v18, v84
	v_sub_f32_e32 v19, v19, v84
	v_mul_f32_e32 v18, v18, v85
	v_mul_f32_e32 v19, v19, v85
	v_fma_f32 v18, v18, v130, v146
	v_fma_f32 v19, v19, v131, v147
	v_fma_f32 v2, v18, s14, v2
	v_fma_f32 v3, v19, s14, v3
	v_lshlrev_b32_e32 v20, 16, v78
	v_and_b32_e32 v21, 0xffff0000, v78
	v_lshlrev_b32_e32 v4, 16, v70
	v_and_b32_e32 v5, 0xffff0000, v70
	v_sub_f32_e32 v20, v20, v84
	v_sub_f32_e32 v21, v21, v84
	v_mul_f32_e32 v20, v20, v85
	v_mul_f32_e32 v21, v21, v85
	v_fma_f32 v20, v20, v132, v148
	v_fma_f32 v21, v21, v133, v149
	v_fma_f32 v4, v20, s14, v4
	v_fma_f32 v5, v21, s14, v5
	v_lshlrev_b32_e32 v22, 16, v79
	v_and_b32_e32 v23, 0xffff0000, v79
	v_lshlrev_b32_e32 v6, 16, v71
	v_and_b32_e32 v7, 0xffff0000, v71
	v_sub_f32_e32 v22, v22, v84
	v_sub_f32_e32 v23, v23, v84
	v_mul_f32_e32 v22, v22, v85
	v_mul_f32_e32 v23, v23, v85
	v_fma_f32 v22, v22, v134, v150
	v_fma_f32 v23, v23, v135, v151
	v_fma_f32 v6, v22, s14, v6
	v_fma_f32 v7, v23, s14, v7
	v_lshlrev_b32_e32 v24, 16, v80
	v_and_b32_e32 v25, 0xffff0000, v80
	v_lshlrev_b32_e32 v8, 16, v72
	v_and_b32_e32 v9, 0xffff0000, v72
	v_sub_f32_e32 v24, v24, v84
	v_sub_f32_e32 v25, v25, v84
	v_mul_f32_e32 v24, v24, v85
	v_mul_f32_e32 v25, v25, v85
	v_fma_f32 v24, v24, v136, v152
	v_fma_f32 v25, v25, v137, v153
	v_fma_f32 v8, v24, s14, v8
	v_fma_f32 v9, v25, s14, v9
	v_lshlrev_b32_e32 v26, 16, v81
	v_and_b32_e32 v27, 0xffff0000, v81
	v_lshlrev_b32_e32 v10, 16, v73
	v_and_b32_e32 v11, 0xffff0000, v73
	v_sub_f32_e32 v26, v26, v84
	v_sub_f32_e32 v27, v27, v84
	v_mul_f32_e32 v26, v26, v85
	v_mul_f32_e32 v27, v27, v85
	v_fma_f32 v26, v26, v138, v154
	v_fma_f32 v27, v27, v139, v155
	v_fma_f32 v10, v26, s14, v10
	v_fma_f32 v11, v27, s14, v11
	v_lshlrev_b32_e32 v28, 16, v82
	v_and_b32_e32 v29, 0xffff0000, v82
	v_lshlrev_b32_e32 v12, 16, v74
	v_and_b32_e32 v13, 0xffff0000, v74
	v_sub_f32_e32 v28, v28, v84
	v_sub_f32_e32 v29, v29, v84
	v_mul_f32_e32 v28, v28, v85
	v_mul_f32_e32 v29, v29, v85
	v_fma_f32 v28, v28, v140, v156
	v_fma_f32 v29, v29, v141, v157
	v_fma_f32 v12, v28, s14, v12
	v_fma_f32 v13, v29, s14, v13
	v_lshlrev_b32_e32 v30, 16, v83
	v_and_b32_e32 v31, 0xffff0000, v83
	v_lshlrev_b32_e32 v14, 16, v75
	v_and_b32_e32 v15, 0xffff0000, v75
	v_sub_f32_e32 v30, v30, v84
	v_sub_f32_e32 v31, v31, v84
	v_mul_f32_e32 v30, v30, v85
	v_mul_f32_e32 v31, v31, v85
	v_fma_f32 v30, v30, v142, v158
	v_fma_f32 v31, v31, v143, v159
	v_fma_f32 v14, v30, s14, v14
	v_fma_f32 v15, v31, s14, v15
	v_add_f32_e32 v16, v0, v1
	v_add_f32_e32 v17, v2, v3
	v_add_f32_e32 v18, v4, v5
	v_add_f32_e32 v19, v6, v7
	v_add_f32_e32 v20, v8, v9
	v_add_f32_e32 v21, v10, v11
	v_add_f32_e32 v22, v12, v13
	v_add_f32_e32 v23, v14, v15
	v_add_f32_e32 v16, v16, v17
	v_add_f32_e32 v18, v18, v19
	v_add_f32_e32 v20, v20, v21
	v_add_f32_e32 v22, v22, v23
	v_add_f32_e32 v16, v16, v18
	v_add_f32_e32 v20, v20, v22
	v_add_f32_e32 v32, v16, v20
	v_mov_b32_e32 v34, v32
	s_nop 1
	v_add_f32_dpp v34, v32, v32 quad_perm:[1,0,3,2] row_mask:0xf bank_mask:0xf
	s_nop 1
	v_add_f32_dpp v34, v34, v34 quad_perm:[2,3,0,1] row_mask:0xf bank_mask:0xf
	s_nop 1
	v_add_f32_dpp v34, v34, v34 row_half_mirror row_mask:0xf bank_mask:0xf
	s_nop 1
	v_add_f32_dpp v34, v34, v34 row_mirror row_mask:0xf bank_mask:0xf
	s_nop 1
	v_add_f32_dpp v34, v34, v34 row_bcast:15 row_mask:0xa bank_mask:0xf
	s_nop 1
	v_add_f32_dpp v34, v34, v34 row_bcast:31 row_mask:0xc bank_mask:0xf
	s_nop 1
	v_readlane_b32 s0, v34, 63
	s_nop 0
	v_mov_b32_e32 v33, 0x3a800000
	v_mul_f32_e32 v33, s0, v33
	v_sub_f32_e32 v0, v0, v33
	v_sub_f32_e32 v1, v1, v33
	v_sub_f32_e32 v2, v2, v33
	v_sub_f32_e32 v3, v3, v33
	v_sub_f32_e32 v4, v4, v33
	v_sub_f32_e32 v5, v5, v33
	v_sub_f32_e32 v6, v6, v33
	v_sub_f32_e32 v7, v7, v33
	v_sub_f32_e32 v8, v8, v33
	v_sub_f32_e32 v9, v9, v33
	v_sub_f32_e32 v10, v10, v33
	v_sub_f32_e32 v11, v11, v33
	v_sub_f32_e32 v12, v12, v33
	v_sub_f32_e32 v13, v13, v33
	v_sub_f32_e32 v14, v14, v33
	v_sub_f32_e32 v15, v15, v33
	v_mul_f32_e32 v16, v0, v0
	v_fmac_f32_e32 v16, v1, v1
	v_mul_f32_e32 v17, v2, v2
	v_fmac_f32_e32 v17, v3, v3
	v_mul_f32_e32 v18, v4, v4
	v_fmac_f32_e32 v18, v5, v5
	v_mul_f32_e32 v19, v6, v6
	v_fmac_f32_e32 v19, v7, v7
	v_mul_f32_e32 v20, v8, v8
	v_fmac_f32_e32 v20, v9, v9
	v_mul_f32_e32 v21, v10, v10
	v_fmac_f32_e32 v21, v11, v11
	v_mul_f32_e32 v22, v12, v12
	v_fmac_f32_e32 v22, v13, v13
	v_mul_f32_e32 v23, v14, v14
	v_fmac_f32_e32 v23, v15, v15
	v_add_f32_e32 v16, v16, v17
	v_add_f32_e32 v18, v18, v19
	v_add_f32_e32 v20, v20, v21
	v_add_f32_e32 v22, v22, v23
	v_add_f32_e32 v16, v16, v18
	v_add_f32_e32 v20, v20, v22
	v_add_f32_e32 v32, v16, v20
	v_mov_b32_e32 v34, v32
	s_nop 1
	v_add_f32_dpp v34, v32, v32 quad_perm:[1,0,3,2] row_mask:0xf bank_mask:0xf
	s_nop 1
	v_add_f32_dpp v34, v34, v34 quad_perm:[2,3,0,1] row_mask:0xf bank_mask:0xf
	s_nop 1
	v_add_f32_dpp v34, v34, v34 row_half_mirror row_mask:0xf bank_mask:0xf
	s_nop 1
	v_add_f32_dpp v34, v34, v34 row_mirror row_mask:0xf bank_mask:0xf
	s_nop 1
	v_add_f32_dpp v34, v34, v34 row_bcast:15 row_mask:0xa bank_mask:0xf
	s_nop 1
	v_add_f32_dpp v34, v34, v34 row_bcast:31 row_mask:0xc bank_mask:0xf
	s_nop 1
	v_readlane_b32 s0, v34, 63
	s_nop 0
	v_mov_b32_e32 v33, 0x3a800000
	v_mov_b32_e32 v35, 0x3727c5ac
	v_fma_f32 v33, s0, v33, v35
	v_rsq_f32_e32 v33, v33
	s_nop 0
	v_mul_f32_e32 v0, v0, v33
	v_mul_f32_e32 v1, v1, v33
	v_mul_f32_e32 v2, v2, v33
	v_mul_f32_e32 v3, v3, v33
	v_fma_f32 v0, v0, v160, v176
	v_fma_f32 v1, v1, v161, v177
	v_fma_f32 v2, v2, v162, v178
	v_fma_f32 v3, v3, v163, v179
	v_mul_f32_e32 v4, v4, v33
	v_mul_f32_e32 v5, v5, v33
	v_mul_f32_e32 v6, v6, v33
	v_mul_f32_e32 v7, v7, v33
	v_fma_f32 v4, v4, v164, v180
	v_fma_f32 v5, v5, v165, v181
	v_fma_f32 v6, v6, v166, v182
	v_fma_f32 v7, v7, v167, v183
	v_mul_f32_e32 v8, v8, v33
	v_mul_f32_e32 v9, v9, v33
	v_mul_f32_e32 v10, v10, v33
	v_mul_f32_e32 v11, v11, v33
	v_fma_f32 v8, v8, v168, v184
	v_fma_f32 v9, v9, v169, v185
	v_fma_f32 v10, v10, v170, v186
	v_fma_f32 v11, v11, v171, v187
	v_mul_f32_e32 v12, v12, v33
	v_mul_f32_e32 v13, v13, v33
	v_mul_f32_e32 v14, v14, v33
	v_mul_f32_e32 v15, v15, v33
	v_fma_f32 v12, v12, v172, v188
	v_fma_f32 v13, v13, v173, v189
	v_fma_f32 v14, v14, v174, v190
	v_fma_f32 v15, v15, v175, v191
	global_store_dwordx4 v[238:239], v[0:3], off
	global_store_dwordx4 v[238:239], v[4:7], off offset:16
	global_store_dwordx4 v[238:239], v[8:11], off offset:2048
	global_store_dwordx4 v[238:239], v[12:15], off offset:2064
	s_mov_b32 s44, 0x800000
	s_mov_b32 s45, 0
	v_lshl_add_u64 v[238:239], v[238:239], 0, s[44:45]
	s_add_u32 s33, s33, 1
	global_load_dwordx4 v[68:71], v[232:233], off
	global_load_dwordx4 v[72:75], v[232:233], off offset:1024
	global_load_dwordx4 v[76:79], v[234:235], off
	global_load_dwordx4 v[80:83], v[234:235], off offset:1024
	global_load_dwordx2 v[84:85], v[236:237], off
	s_cmp_lt_u32 s33, 28
	s_cselect_b32 s44, s40, 0
	s_cselect_b32 s46, s42, 0
	s_mov_b32 s45, 0
	s_mov_b32 s47, 0
	v_lshl_add_u64 v[232:233], v[232:233], 0, s[44:45]
	v_lshl_add_u64 v[234:235], v[234:235], 0, s[44:45]
	v_lshl_add_u64 v[236:237], v[236:237], 0, s[46:47]
	s_waitcnt vmcnt(27)
	v_lshlrev_b32_e32 v16, 16, v96
	v_and_b32_e32 v17, 0xffff0000, v96
	v_lshlrev_b32_e32 v0, 16, v88
	v_and_b32_e32 v1, 0xffff0000, v88
	v_sub_f32_e32 v16, v16, v104
	v_sub_f32_e32 v17, v17, v104
	v_mul_f32_e32 v16, v16, v105
	v_mul_f32_e32 v17, v17, v105
	v_fma_f32 v16, v16, v128, v144
	v_fma_f32 v17, v17, v129, v145
	v_fma_f32 v0, v16, s14, v0
	v_fma_f32 v1, v17, s14, v1
	v_lshlrev_b32_e32 v18, 16, v97
	v_and_b32_e32 v19, 0xffff0000, v97
	v_lshlrev_b32_e32 v2, 16, v89
	v_and_b32_e32 v3, 0xffff0000, v89
	v_sub_f32_e32 v18, v18, v104
	v_sub_f32_e32 v19, v19, v104
	v_mul_f32_e32 v18, v18, v105
	v_mul_f32_e32 v19, v19, v105
	v_fma_f32 v18, v18, v130, v146
	v_fma_f32 v19, v19, v131, v147
	v_fma_f32 v2, v18, s14, v2
	v_fma_f32 v3, v19, s14, v3
	v_lshlrev_b32_e32 v20, 16, v98
	v_and_b32_e32 v21, 0xffff0000, v98
	v_lshlrev_b32_e32 v4, 16, v90
	v_and_b32_e32 v5, 0xffff0000, v90
	v_sub_f32_e32 v20, v20, v104
	v_sub_f32_e32 v21, v21, v104
	v_mul_f32_e32 v20, v20, v105
	v_mul_f32_e32 v21, v21, v105
	v_fma_f32 v20, v20, v132, v148
	v_fma_f32 v21, v21, v133, v149
	v_fma_f32 v4, v20, s14, v4
	v_fma_f32 v5, v21, s14, v5
	v_lshlrev_b32_e32 v22, 16, v99
	v_and_b32_e32 v23, 0xffff0000, v99
	v_lshlrev_b32_e32 v6, 16, v91
	v_and_b32_e32 v7, 0xffff0000, v91
	v_sub_f32_e32 v22, v22, v104
	v_sub_f32_e32 v23, v23, v104
	v_mul_f32_e32 v22, v22, v105
	v_mul_f32_e32 v23, v23, v105
	v_fma_f32 v22, v22, v134, v150
	v_fma_f32 v23, v23, v135, v151
	v_fma_f32 v6, v22, s14, v6
	v_fma_f32 v7, v23, s14, v7
	v_lshlrev_b32_e32 v24, 16, v100
	v_and_b32_e32 v25, 0xffff0000, v100
	v_lshlrev_b32_e32 v8, 16, v92
	v_and_b32_e32 v9, 0xffff0000, v92
	v_sub_f32_e32 v24, v24, v104
	v_sub_f32_e32 v25, v25, v104
	v_mul_f32_e32 v24, v24, v105
	v_mul_f32_e32 v25, v25, v105
	v_fma_f32 v24, v24, v136, v152
	v_fma_f32 v25, v25, v137, v153
	v_fma_f32 v8, v24, s14, v8
	v_fma_f32 v9, v25, s14, v9
	v_lshlrev_b32_e32 v26, 16, v101
	v_and_b32_e32 v27, 0xffff0000, v101
	v_lshlrev_b32_e32 v10, 16, v93
	v_and_b32_e32 v11, 0xffff0000, v93
	v_sub_f32_e32 v26, v26, v104
	v_sub_f32_e32 v27, v27, v104
	v_mul_f32_e32 v26, v26, v105
	v_mul_f32_e32 v27, v27, v105
	v_fma_f32 v26, v26, v138, v154
	v_fma_f32 v27, v27, v139, v155
	v_fma_f32 v10, v26, s14, v10
	v_fma_f32 v11, v27, s14, v11
	v_lshlrev_b32_e32 v28, 16, v102
	v_and_b32_e32 v29, 0xffff0000, v102
	v_lshlrev_b32_e32 v12, 16, v94
	v_and_b32_e32 v13, 0xffff0000, v94
	v_sub_f32_e32 v28, v28, v104
	v_sub_f32_e32 v29, v29, v104
	v_mul_f32_e32 v28, v28, v105
	v_mul_f32_e32 v29, v29, v105
	v_fma_f32 v28, v28, v140, v156
	v_fma_f32 v29, v29, v141, v157
	v_fma_f32 v12, v28, s14, v12
	v_fma_f32 v13, v29, s14, v13
	v_lshlrev_b32_e32 v30, 16, v103
	v_and_b32_e32 v31, 0xffff0000, v103
	v_lshlrev_b32_e32 v14, 16, v95
	v_and_b32_e32 v15, 0xffff0000, v95
	v_sub_f32_e32 v30, v30, v104
	v_sub_f32_e32 v31, v31, v104
	v_mul_f32_e32 v30, v30, v105
	v_mul_f32_e32 v31, v31, v105
	v_fma_f32 v30, v30, v142, v158
	v_fma_f32 v31, v31, v143, v159
	v_fma_f32 v14, v30, s14, v14
	v_fma_f32 v15, v31, s14, v15
	v_add_f32_e32 v16, v0, v1
	v_add_f32_e32 v17, v2, v3
	v_add_f32_e32 v18, v4, v5
	v_add_f32_e32 v19, v6, v7
	v_add_f32_e32 v20, v8, v9
	v_add_f32_e32 v21, v10, v11
	v_add_f32_e32 v22, v12, v13
	v_add_f32_e32 v23, v14, v15
	v_add_f32_e32 v16, v16, v17
	v_add_f32_e32 v18, v18, v19
	v_add_f32_e32 v20, v20, v21
	v_add_f32_e32 v22, v22, v23
	v_add_f32_e32 v16, v16, v18
	v_add_f32_e32 v20, v20, v22
	v_add_f32_e32 v32, v16, v20
	v_mov_b32_e32 v34, v32
	s_nop 1
	v_add_f32_dpp v34, v32, v32 quad_perm:[1,0,3,2] row_mask:0xf bank_mask:0xf
	s_nop 1
	v_add_f32_dpp v34, v34, v34 quad_perm:[2,3,0,1] row_mask:0xf bank_mask:0xf
	s_nop 1
	v_add_f32_dpp v34, v34, v34 row_half_mirror row_mask:0xf bank_mask:0xf
	s_nop 1
	v_add_f32_dpp v34, v34, v34 row_mirror row_mask:0xf bank_mask:0xf
	s_nop 1
	v_add_f32_dpp v34, v34, v34 row_bcast:15 row_mask:0xa bank_mask:0xf
	s_nop 1
	v_add_f32_dpp v34, v34, v34 row_bcast:31 row_mask:0xc bank_mask:0xf
	s_nop 1
	v_readlane_b32 s0, v34, 63
	s_nop 0
	v_mov_b32_e32 v33, 0x3a800000
	v_mul_f32_e32 v33, s0, v33
	v_sub_f32_e32 v0, v0, v33
	v_sub_f32_e32 v1, v1, v33
	v_sub_f32_e32 v2, v2, v33
	v_sub_f32_e32 v3, v3, v33
	v_sub_f32_e32 v4, v4, v33
	v_sub_f32_e32 v5, v5, v33
	v_sub_f32_e32 v6, v6, v33
	v_sub_f32_e32 v7, v7, v33
	v_sub_f32_e32 v8, v8, v33
	v_sub_f32_e32 v9, v9, v33
	v_sub_f32_e32 v10, v10, v33
	v_sub_f32_e32 v11, v11, v33
	v_sub_f32_e32 v12, v12, v33
	v_sub_f32_e32 v13, v13, v33
	v_sub_f32_e32 v14, v14, v33
	v_sub_f32_e32 v15, v15, v33
	v_mul_f32_e32 v16, v0, v0
	v_fmac_f32_e32 v16, v1, v1
	v_mul_f32_e32 v17, v2, v2
	v_fmac_f32_e32 v17, v3, v3
	v_mul_f32_e32 v18, v4, v4
	v_fmac_f32_e32 v18, v5, v5
	v_mul_f32_e32 v19, v6, v6
	v_fmac_f32_e32 v19, v7, v7
	v_mul_f32_e32 v20, v8, v8
	v_fmac_f32_e32 v20, v9, v9
	v_mul_f32_e32 v21, v10, v10
	v_fmac_f32_e32 v21, v11, v11
	v_mul_f32_e32 v22, v12, v12
	v_fmac_f32_e32 v22, v13, v13
	v_mul_f32_e32 v23, v14, v14
	v_fmac_f32_e32 v23, v15, v15
	v_add_f32_e32 v16, v16, v17
	v_add_f32_e32 v18, v18, v19
	v_add_f32_e32 v20, v20, v21
	v_add_f32_e32 v22, v22, v23
	v_add_f32_e32 v16, v16, v18
	v_add_f32_e32 v20, v20, v22
	v_add_f32_e32 v32, v16, v20
	v_mov_b32_e32 v34, v32
	s_nop 1
	v_add_f32_dpp v34, v32, v32 quad_perm:[1,0,3,2] row_mask:0xf bank_mask:0xf
	s_nop 1
	v_add_f32_dpp v34, v34, v34 quad_perm:[2,3,0,1] row_mask:0xf bank_mask:0xf
	s_nop 1
	v_add_f32_dpp v34, v34, v34 row_half_mirror row_mask:0xf bank_mask:0xf
	s_nop 1
	v_add_f32_dpp v34, v34, v34 row_mirror row_mask:0xf bank_mask:0xf
	s_nop 1
	v_add_f32_dpp v34, v34, v34 row_bcast:15 row_mask:0xa bank_mask:0xf
	s_nop 1
	v_add_f32_dpp v34, v34, v34 row_bcast:31 row_mask:0xc bank_mask:0xf
	s_nop 1
	v_readlane_b32 s0, v34, 63
	s_nop 0
	v_mov_b32_e32 v33, 0x3a800000
	v_mov_b32_e32 v35, 0x3727c5ac
	v_fma_f32 v33, s0, v33, v35
	v_rsq_f32_e32 v33, v33
	s_nop 0
	v_mul_f32_e32 v0, v0, v33
	v_mul_f32_e32 v1, v1, v33
	v_mul_f32_e32 v2, v2, v33
	v_mul_f32_e32 v3, v3, v33
	v_fma_f32 v0, v0, v160, v176
	v_fma_f32 v1, v1, v161, v177
	v_fma_f32 v2, v2, v162, v178
	v_fma_f32 v3, v3, v163, v179
	v_mul_f32_e32 v4, v4, v33
	v_mul_f32_e32 v5, v5, v33
	v_mul_f32_e32 v6, v6, v33
	v_mul_f32_e32 v7, v7, v33
	v_fma_f32 v4, v4, v164, v180
	v_fma_f32 v5, v5, v165, v181
	v_fma_f32 v6, v6, v166, v182
	v_fma_f32 v7, v7, v167, v183
	v_mul_f32_e32 v8, v8, v33
	v_mul_f32_e32 v9, v9, v33
	v_mul_f32_e32 v10, v10, v33
	v_mul_f32_e32 v11, v11, v33
	v_fma_f32 v8, v8, v168, v184
	v_fma_f32 v9, v9, v169, v185
	v_fma_f32 v10, v10, v170, v186
	v_fma_f32 v11, v11, v171, v187
	v_mul_f32_e32 v12, v12, v33
	v_mul_f32_e32 v13, v13, v33
	v_mul_f32_e32 v14, v14, v33
	v_mul_f32_e32 v15, v15, v33
	v_fma_f32 v12, v12, v172, v188
	v_fma_f32 v13, v13, v173, v189
	v_fma_f32 v14, v14, v174, v190
	v_fma_f32 v15, v15, v175, v191
	global_store_dwordx4 v[238:239], v[0:3], off
	global_store_dwordx4 v[238:239], v[4:7], off offset:16
	global_store_dwordx4 v[238:239], v[8:11], off offset:2048
	global_store_dwordx4 v[238:239], v[12:15], off offset:2064
	s_mov_b32 s44, 0x800000
	s_mov_b32 s45, 0
	v_lshl_add_u64 v[238:239], v[238:239], 0, s[44:45]
	s_add_u32 s33, s33, 1
	global_load_dwordx4 v[88:91], v[232:233], off
	global_load_dwordx4 v[92:95], v[232:233], off offset:1024
	global_load_dwordx4 v[96:99], v[234:235], off
	global_load_dwordx4 v[100:103], v[234:235], off offset:1024
	global_load_dwordx2 v[104:105], v[236:237], off
	s_cmp_lt_u32 s33, 28
	s_cselect_b32 s44, s40, 0
	s_cselect_b32 s46, s42, 0
	s_mov_b32 s45, 0
	s_mov_b32 s47, 0
	v_lshl_add_u64 v[232:233], v[232:233], 0, s[44:45]
	v_lshl_add_u64 v[234:235], v[234:235], 0, s[44:45]
	v_lshl_add_u64 v[236:237], v[236:237], 0, s[46:47]
	s_waitcnt vmcnt(27)
	v_lshlrev_b32_e32 v16, 16, v116
	v_and_b32_e32 v17, 0xffff0000, v116
	v_lshlrev_b32_e32 v0, 16, v108
	v_and_b32_e32 v1, 0xffff0000, v108
	v_sub_f32_e32 v16, v16, v124
	v_sub_f32_e32 v17, v17, v124
	v_mul_f32_e32 v16, v16, v125
	v_mul_f32_e32 v17, v17, v125
	v_fma_f32 v16, v16, v128, v144
	v_fma_f32 v17, v17, v129, v145
	v_fma_f32 v0, v16, s14, v0
	v_fma_f32 v1, v17, s14, v1
	v_lshlrev_b32_e32 v18, 16, v117
	v_and_b32_e32 v19, 0xffff0000, v117
	v_lshlrev_b32_e32 v2, 16, v109
	v_and_b32_e32 v3, 0xffff0000, v109
	v_sub_f32_e32 v18, v18, v124
	v_sub_f32_e32 v19, v19, v124
	v_mul_f32_e32 v18, v18, v125
	v_mul_f32_e32 v19, v19, v125
	v_fma_f32 v18, v18, v130, v146
	v_fma_f32 v19, v19, v131, v147
	v_fma_f32 v2, v18, s14, v2
	v_fma_f32 v3, v19, s14, v3
	v_lshlrev_b32_e32 v20, 16, v118
	v_and_b32_e32 v21, 0xffff0000, v118
	v_lshlrev_b32_e32 v4, 16, v110
	v_and_b32_e32 v5, 0xffff0000, v110
	v_sub_f32_e32 v20, v20, v124
	v_sub_f32_e32 v21, v21, v124
	v_mul_f32_e32 v20, v20, v125
	v_mul_f32_e32 v21, v21, v125
	v_fma_f32 v20, v20, v132, v148
	v_fma_f32 v21, v21, v133, v149
	v_fma_f32 v4, v20, s14, v4
	v_fma_f32 v5, v21, s14, v5
	v_lshlrev_b32_e32 v22, 16, v119
	v_and_b32_e32 v23, 0xffff0000, v119
	v_lshlrev_b32_e32 v6, 16, v111
	v_and_b32_e32 v7, 0xffff0000, v111
	v_sub_f32_e32 v22, v22, v124
	v_sub_f32_e32 v23, v23, v124
	v_mul_f32_e32 v22, v22, v125
	v_mul_f32_e32 v23, v23, v125
	v_fma_f32 v22, v22, v134, v150
	v_fma_f32 v23, v23, v135, v151
	v_fma_f32 v6, v22, s14, v6
	v_fma_f32 v7, v23, s14, v7
	v_lshlrev_b32_e32 v24, 16, v120
	v_and_b32_e32 v25, 0xffff0000, v120
	v_lshlrev_b32_e32 v8, 16, v112
	v_and_b32_e32 v9, 0xffff0000, v112
	v_sub_f32_e32 v24, v24, v124
	v_sub_f32_e32 v25, v25, v124
	v_mul_f32_e32 v24, v24, v125
	v_mul_f32_e32 v25, v25, v125
	v_fma_f32 v24, v24, v136, v152
	v_fma_f32 v25, v25, v137, v153
	v_fma_f32 v8, v24, s14, v8
	v_fma_f32 v9, v25, s14, v9
	v_lshlrev_b32_e32 v26, 16, v121
	v_and_b32_e32 v27, 0xffff0000, v121
	v_lshlrev_b32_e32 v10, 16, v113
	v_and_b32_e32 v11, 0xffff0000, v113
	v_sub_f32_e32 v26, v26, v124
	v_sub_f32_e32 v27, v27, v124
	v_mul_f32_e32 v26, v26, v125
	v_mul_f32_e32 v27, v27, v125
	v_fma_f32 v26, v26, v138, v154
	v_fma_f32 v27, v27, v139, v155
	v_fma_f32 v10, v26, s14, v10
	v_fma_f32 v11, v27, s14, v11
	v_lshlrev_b32_e32 v28, 16, v122
	v_and_b32_e32 v29, 0xffff0000, v122
	v_lshlrev_b32_e32 v12, 16, v114
	v_and_b32_e32 v13, 0xffff0000, v114
	v_sub_f32_e32 v28, v28, v124
	v_sub_f32_e32 v29, v29, v124
	v_mul_f32_e32 v28, v28, v125
	v_mul_f32_e32 v29, v29, v125
	v_fma_f32 v28, v28, v140, v156
	v_fma_f32 v29, v29, v141, v157
	v_fma_f32 v12, v28, s14, v12
	v_fma_f32 v13, v29, s14, v13
	v_lshlrev_b32_e32 v30, 16, v123
	v_and_b32_e32 v31, 0xffff0000, v123
	v_lshlrev_b32_e32 v14, 16, v115
	v_and_b32_e32 v15, 0xffff0000, v115
	v_sub_f32_e32 v30, v30, v124
	v_sub_f32_e32 v31, v31, v124
	v_mul_f32_e32 v30, v30, v125
	v_mul_f32_e32 v31, v31, v125
	v_fma_f32 v30, v30, v142, v158
	v_fma_f32 v31, v31, v143, v159
	v_fma_f32 v14, v30, s14, v14
	v_fma_f32 v15, v31, s14, v15
	v_add_f32_e32 v16, v0, v1
	v_add_f32_e32 v17, v2, v3
	v_add_f32_e32 v18, v4, v5
	v_add_f32_e32 v19, v6, v7
	v_add_f32_e32 v20, v8, v9
	v_add_f32_e32 v21, v10, v11
	v_add_f32_e32 v22, v12, v13
	v_add_f32_e32 v23, v14, v15
	v_add_f32_e32 v16, v16, v17
	v_add_f32_e32 v18, v18, v19
	v_add_f32_e32 v20, v20, v21
	v_add_f32_e32 v22, v22, v23
	v_add_f32_e32 v16, v16, v18
	v_add_f32_e32 v20, v20, v22
	v_add_f32_e32 v32, v16, v20
	v_mov_b32_e32 v34, v32
	s_nop 1
	v_add_f32_dpp v34, v32, v32 quad_perm:[1,0,3,2] row_mask:0xf bank_mask:0xf
	s_nop 1
	v_add_f32_dpp v34, v34, v34 quad_perm:[2,3,0,1] row_mask:0xf bank_mask:0xf
	s_nop 1
	v_add_f32_dpp v34, v34, v34 row_half_mirror row_mask:0xf bank_mask:0xf
	s_nop 1
	v_add_f32_dpp v34, v34, v34 row_mirror row_mask:0xf bank_mask:0xf
	s_nop 1
	v_add_f32_dpp v34, v34, v34 row_bcast:15 row_mask:0xa bank_mask:0xf
	s_nop 1
	v_add_f32_dpp v34, v34, v34 row_bcast:31 row_mask:0xc bank_mask:0xf
	s_nop 1
	v_readlane_b32 s0, v34, 63
	s_nop 0
	v_mov_b32_e32 v33, 0x3a800000
	v_mul_f32_e32 v33, s0, v33
	v_sub_f32_e32 v0, v0, v33
	v_sub_f32_e32 v1, v1, v33
	v_sub_f32_e32 v2, v2, v33
	v_sub_f32_e32 v3, v3, v33
	v_sub_f32_e32 v4, v4, v33
	v_sub_f32_e32 v5, v5, v33
	v_sub_f32_e32 v6, v6, v33
	v_sub_f32_e32 v7, v7, v33
	v_sub_f32_e32 v8, v8, v33
	v_sub_f32_e32 v9, v9, v33
	v_sub_f32_e32 v10, v10, v33
	v_sub_f32_e32 v11, v11, v33
	v_sub_f32_e32 v12, v12, v33
	v_sub_f32_e32 v13, v13, v33
	v_sub_f32_e32 v14, v14, v33
	v_sub_f32_e32 v15, v15, v33
	v_mul_f32_e32 v16, v0, v0
	v_fmac_f32_e32 v16, v1, v1
	v_mul_f32_e32 v17, v2, v2
	v_fmac_f32_e32 v17, v3, v3
	v_mul_f32_e32 v18, v4, v4
	v_fmac_f32_e32 v18, v5, v5
	v_mul_f32_e32 v19, v6, v6
	v_fmac_f32_e32 v19, v7, v7
	v_mul_f32_e32 v20, v8, v8
	v_fmac_f32_e32 v20, v9, v9
	v_mul_f32_e32 v21, v10, v10
	v_fmac_f32_e32 v21, v11, v11
	v_mul_f32_e32 v22, v12, v12
	v_fmac_f32_e32 v22, v13, v13
	v_mul_f32_e32 v23, v14, v14
	v_fmac_f32_e32 v23, v15, v15
	v_add_f32_e32 v16, v16, v17
	v_add_f32_e32 v18, v18, v19
	v_add_f32_e32 v20, v20, v21
	v_add_f32_e32 v22, v22, v23
	v_add_f32_e32 v16, v16, v18
	v_add_f32_e32 v20, v20, v22
	v_add_f32_e32 v32, v16, v20
	v_mov_b32_e32 v34, v32
	s_nop 1
	v_add_f32_dpp v34, v32, v32 quad_perm:[1,0,3,2] row_mask:0xf bank_mask:0xf
	s_nop 1
	v_add_f32_dpp v34, v34, v34 quad_perm:[2,3,0,1] row_mask:0xf bank_mask:0xf
	s_nop 1
	v_add_f32_dpp v34, v34, v34 row_half_mirror row_mask:0xf bank_mask:0xf
	s_nop 1
	v_add_f32_dpp v34, v34, v34 row_mirror row_mask:0xf bank_mask:0xf
	s_nop 1
	v_add_f32_dpp v34, v34, v34 row_bcast:15 row_mask:0xa bank_mask:0xf
	s_nop 1
	v_add_f32_dpp v34, v34, v34 row_bcast:31 row_mask:0xc bank_mask:0xf
	s_nop 1
	v_readlane_b32 s0, v34, 63
	s_nop 0
	v_mov_b32_e32 v33, 0x3a800000
	v_mov_b32_e32 v35, 0x3727c5ac
	v_fma_f32 v33, s0, v33, v35
	v_rsq_f32_e32 v33, v33
	s_nop 0
	v_mul_f32_e32 v0, v0, v33
	v_mul_f32_e32 v1, v1, v33
	v_mul_f32_e32 v2, v2, v33
	v_mul_f32_e32 v3, v3, v33
	v_fma_f32 v0, v0, v160, v176
	v_fma_f32 v1, v1, v161, v177
	v_fma_f32 v2, v2, v162, v178
	v_fma_f32 v3, v3, v163, v179
	v_mul_f32_e32 v4, v4, v33
	v_mul_f32_e32 v5, v5, v33
	v_mul_f32_e32 v6, v6, v33
	v_mul_f32_e32 v7, v7, v33
	v_fma_f32 v4, v4, v164, v180
	v_fma_f32 v5, v5, v165, v181
	v_fma_f32 v6, v6, v166, v182
	v_fma_f32 v7, v7, v167, v183
	v_mul_f32_e32 v8, v8, v33
	v_mul_f32_e32 v9, v9, v33
	v_mul_f32_e32 v10, v10, v33
	v_mul_f32_e32 v11, v11, v33
	v_fma_f32 v8, v8, v168, v184
	v_fma_f32 v9, v9, v169, v185
	v_fma_f32 v10, v10, v170, v186
	v_fma_f32 v11, v11, v171, v187
	v_mul_f32_e32 v12, v12, v33
	v_mul_f32_e32 v13, v13, v33
	v_mul_f32_e32 v14, v14, v33
	v_mul_f32_e32 v15, v15, v33
	v_fma_f32 v12, v12, v172, v188
	v_fma_f32 v13, v13, v173, v189
	v_fma_f32 v14, v14, v174, v190
	v_fma_f32 v15, v15, v175, v191
	global_store_dwordx4 v[238:239], v[0:3], off
	global_store_dwordx4 v[238:239], v[4:7], off offset:16
	global_store_dwordx4 v[238:239], v[8:11], off offset:2048
	global_store_dwordx4 v[238:239], v[12:15], off offset:2064
	s_mov_b32 s44, 0x800000
	s_mov_b32 s45, 0
	v_lshl_add_u64 v[238:239], v[238:239], 0, s[44:45]
	s_add_u32 s33, s33, 1
	s_cmp_lt_u32 s33, 32
	s_cbranch_scc1 .Lln2_loop
	s_endpgm
